# phase 11 final RMSNorm loop hand-pipelined: next-row prefetch, hoisted weights, DPP reduce, no store waits
# speedup vs baseline: 1.0191x; 1.0191x over previous
; __device__ __forceinline__ float bf_lo(unsigned u) { return __uint_as_float(u << 16); }
; __device__ __forceinline__ float bf_hi(unsigned u) { return __uint_as_float(u & 0xffff0000u); }
; __device__ void phase_final(const Params& p) {
;     const int lane = threadIdx.x & 63, w = threadIdx.x >> 6;
;     const bf16_t* x3 = (const bf16_t*)(p.ws + WS_B0);
;     for (int r = blockIdx.x * 8 + w; r < T; r += gridDim.x * 8) {
;         const bf16_t* src = x3 + (size_t)r * D;
;         float* row = p.out + (size_t)r * D;
;         u32x4 v[4]; float ss = 0.f;
; #pragma unroll
;         for (int i = 0; i < 4; ++i) {
;             v[i] = __builtin_nontemporal_load((const u32x4*)(src + i * 512 + lane * 8));
;             const float a0 = bf_lo(v[i].x), a1 = bf_hi(v[i].x), a2 = bf_lo(v[i].y), a3 = bf_hi(v[i].y), a4 = bf_lo(v[i].z), a5 = bf_hi(v[i].z), a6 = bf_lo(v[i].w), a7 = bf_hi(v[i].w);
;             ss += a0 * a0 + a1 * a1 + a2 * a2 + a3 * a3 + a4 * a4 + a5 * a5 + a6 * a6 + a7 * a7;
;         }
;         ss = wave_sum(ss);
;         const float rstd = rsqrtf(ss * (1.0f / D) + EPS);
.LBB0_1084:
	s_cmp_lt_i32 s74, 12
	s_cselect_b64 s[0:1], -1, 0
	s_and_b64 s[0:1], s[0:1], s[20:21]
	s_andn2_b64 vcc, exec, s[0:1]
	s_cbranch_vccnz .LBB0_1088
	s_waitcnt vmcnt(0)
	v_lshl_add_u32 v0, s78, 3, v176
	s_mov_b32 s0, 0x8000
	v_cmp_gt_i32_e32 vcc, s0, v0
	s_and_saveexec_b64 s[0:1], vcc
	s_cbranch_execz .LBB0_1088
	s_waitcnt lgkmcnt(0)
	v_lshlrev_b32_e32 v1, 3, v206
	v_mbcnt_lo_u32_b32 v4, -1, 0
	v_and_b32_e32 v1, 0x1f8, v1
	v_mbcnt_hi_u32_b32 v4, -1, v4
	v_lshlrev_b32_e32 v6, 1, v1
	v_mov_b32_e32 v7, 0
	v_and_b32_e32 v5, 64, v4
	v_lshl_add_u64 v[2:3], s[44:45], 0, v[6:7]
	v_add_u32_e32 v5, 64, v5
	v_xor_b32_e32 v6, 32, v4
	v_cmp_lt_i32_e32 vcc, v6, v5
	s_load_dword s0, s[96:97], 0xc0
	v_mov_b32_e32 v18, 0x358637bd
	v_cndmask_b32_e32 v6, v4, v6, vcc
	v_lshlrev_b32_e32 v12, 2, v6
	v_xor_b32_e32 v6, 16, v4
	v_cmp_lt_i32_e32 vcc, v6, v5
	s_waitcnt lgkmcnt(0)
	s_lshl_b32 s2, s0, 3
	s_mov_b64 s[0:1], 0x1000
	v_cndmask_b32_e32 v6, v4, v6, vcc
	v_lshlrev_b32_e32 v13, 2, v6
	v_xor_b32_e32 v6, 8, v4
	v_cmp_lt_i32_e32 vcc, v6, v5
	s_mov_b32 s3, 0x800000
	s_movk_i32 s4, 0x1000
	v_cndmask_b32_e32 v6, v4, v6, vcc
	v_lshlrev_b32_e32 v14, 2, v6
	v_xor_b32_e32 v6, 4, v4
	v_cmp_lt_i32_e32 vcc, v6, v5
	s_movk_i32 s5, 0x7fff
	s_nop 0
	v_cndmask_b32_e32 v6, v4, v6, vcc
	v_lshlrev_b32_e32 v15, 2, v6
	v_xor_b32_e32 v6, 2, v4
	v_cmp_lt_i32_e32 vcc, v6, v5
	s_nop 1
	v_cndmask_b32_e32 v6, v4, v6, vcc
	v_lshlrev_b32_e32 v16, 2, v6
	v_xor_b32_e32 v6, 1, v4
	v_cmp_lt_i32_e32 vcc, v6, v5
	s_nop 1
	v_cndmask_b32_e32 v4, v4, v6, vcc
	v_lshlrev_b32_e32 v6, 2, v1
	v_lshlrev_b32_e32 v17, 2, v4
	v_lshl_add_u64 v[4:5], s[70:71], 0, v[6:7]
	v_lshl_add_u64 v[6:7], s[68:69], 0, v[6:7]
	v_lshl_add_u64 v[8:9], v[6:7], 0, s[0:1]
	s_mov_b64 s[0:1], 0x1800
	v_lshl_add_u64 v[10:11], v[6:7], 0, s[0:1]
	s_mov_b64 s[0:1], 0
	v_readfirstlane_b32 s6, v0
	v_lshlrev_b32_e32 v12, 1, v1
	v_lshlrev_b32_e32 v13, 2, v1
	v_add_u32_e32 v14, 0x1000, v13
	s_nop 1
	global_load_dwordx4 v[100:103], v13, s[68:69]
	global_load_dwordx4 v[104:107], v13, s[68:69] offset:16
	global_load_dwordx4 v[108:111], v13, s[68:69] offset:2048
	global_load_dwordx4 v[112:115], v13, s[68:69] offset:2064
	global_load_dwordx4 v[116:119], v14, s[68:69]
	global_load_dwordx4 v[120:123], v14, s[68:69] offset:16
	global_load_dwordx4 v[124:127], v14, s[68:69] offset:2048
	global_load_dwordx4 v[128:131], v14, s[68:69] offset:2064
	s_lshl_b32 s8, s6, 12
	s_add_u32 s10, s44, s8
	s_addc_u32 s11, s45, 0
	global_load_dwordx4 v[20:23], v12, s[10:11] nt
	global_load_dwordx4 v[24:27], v12, s[10:11] offset:1024 nt
	global_load_dwordx4 v[28:31], v12, s[10:11] offset:2048 nt
	global_load_dwordx4 v[32:35], v12, s[10:11] offset:3072 nt
	s_add_i32 s7, s6, s2
	s_cmp_lt_i32 s7, 0x8000
	s_cbranch_scc0 .Lfin_tailA
	s_lshl_b32 s8, s7, 12
	s_add_u32 s10, s44, s8
	s_addc_u32 s11, s45, 0
	global_load_dwordx4 v[36:39], v12, s[10:11] nt
	global_load_dwordx4 v[40:43], v12, s[10:11] offset:1024 nt
	global_load_dwordx4 v[44:47], v12, s[10:11] offset:2048 nt
	global_load_dwordx4 v[48:51], v12, s[10:11] offset:3072 nt
	s_waitcnt vmcnt(4)
	v_lshlrev_b32_e32 v52, 16, v20
	v_and_b32_e32 v53, 0xffff0000, v20
	v_lshlrev_b32_e32 v54, 16, v21
	v_and_b32_e32 v55, 0xffff0000, v21
	v_lshlrev_b32_e32 v56, 16, v22
	v_and_b32_e32 v57, 0xffff0000, v22
	v_lshlrev_b32_e32 v58, 16, v23
	v_and_b32_e32 v59, 0xffff0000, v23
	v_lshlrev_b32_e32 v60, 16, v24
	v_and_b32_e32 v61, 0xffff0000, v24
	v_lshlrev_b32_e32 v62, 16, v25
	v_and_b32_e32 v63, 0xffff0000, v25
	v_lshlrev_b32_e32 v64, 16, v26
	v_and_b32_e32 v65, 0xffff0000, v26
	v_lshlrev_b32_e32 v66, 16, v27
	v_and_b32_e32 v67, 0xffff0000, v27
	v_lshlrev_b32_e32 v68, 16, v28
	v_and_b32_e32 v69, 0xffff0000, v28
	v_lshlrev_b32_e32 v70, 16, v29
	v_and_b32_e32 v71, 0xffff0000, v29
	v_lshlrev_b32_e32 v72, 16, v30
	v_and_b32_e32 v73, 0xffff0000, v30
	v_lshlrev_b32_e32 v74, 16, v31
	v_and_b32_e32 v75, 0xffff0000, v31
	v_lshlrev_b32_e32 v76, 16, v32
	v_and_b32_e32 v77, 0xffff0000, v32
	v_lshlrev_b32_e32 v78, 16, v33
	v_and_b32_e32 v79, 0xffff0000, v33
	v_lshlrev_b32_e32 v80, 16, v34
	v_and_b32_e32 v81, 0xffff0000, v34
	v_lshlrev_b32_e32 v82, 16, v35
	v_and_b32_e32 v83, 0xffff0000, v35
	s_lshl_b32 s8, s6, 13
	s_add_u32 s12, s70, s8
	s_addc_u32 s13, s71, 0
	v_mul_f32_e32 v84, v52, v52
	v_mul_f32_e32 v85, v53, v53
	v_mul_f32_e32 v86, v54, v54
	v_mul_f32_e32 v87, v55, v55
	v_fmac_f32_e32 v84, v56, v56
	v_fmac_f32_e32 v85, v57, v57
	v_fmac_f32_e32 v86, v58, v58
	v_fmac_f32_e32 v87, v59, v59
	v_fmac_f32_e32 v84, v60, v60
	v_fmac_f32_e32 v85, v61, v61
	v_fmac_f32_e32 v86, v62, v62
	v_fmac_f32_e32 v87, v63, v63
	v_fmac_f32_e32 v84, v64, v64
	v_fmac_f32_e32 v85, v65, v65
	v_fmac_f32_e32 v86, v66, v66
	v_fmac_f32_e32 v87, v67, v67
	v_fmac_f32_e32 v84, v68, v68
	v_fmac_f32_e32 v85, v69, v69
	v_fmac_f32_e32 v86, v70, v70
	v_fmac_f32_e32 v87, v71, v71
	v_fmac_f32_e32 v84, v72, v72
	v_fmac_f32_e32 v85, v73, v73
	v_fmac_f32_e32 v86, v74, v74
	v_fmac_f32_e32 v87, v75, v75
	v_fmac_f32_e32 v84, v76, v76
	v_fmac_f32_e32 v85, v77, v77
	v_fmac_f32_e32 v86, v78, v78
	v_fmac_f32_e32 v87, v79, v79
	v_fmac_f32_e32 v84, v80, v80
	v_fmac_f32_e32 v85, v81, v81
	v_fmac_f32_e32 v86, v82, v82
	v_fmac_f32_e32 v87, v83, v83
	v_add_f32_e32 v84, v84, v85
	v_add_f32_e32 v86, v86, v87
	v_add_f32_e32 v84, v84, v86
	s_nop 1
	v_add_f32_dpp v84, v84, v84 quad_perm:[1,0,3,2] row_mask:0xf bank_mask:0xf
	s_nop 1
	v_add_f32_dpp v84, v84, v84 quad_perm:[2,3,0,1] row_mask:0xf bank_mask:0xf
	s_nop 1
	v_add_f32_dpp v84, v84, v84 row_ror:4 row_mask:0xf bank_mask:0xf
	s_nop 1
	v_add_f32_dpp v84, v84, v84 row_ror:8 row_mask:0xf bank_mask:0xf
	s_nop 1
; __device__ __forceinline__ float bf_lo(unsigned u) { return __uint_as_float(u << 16); }
; __device__ __forceinline__ float bf_hi(unsigned u) { return __uint_as_float(u & 0xffff0000u); }
; __device__ void phase_final(const Params& p) {
;     ...
;     for (int r = blockIdx.x * 8 + w; r < T; r += gridDim.x * 8) {
;     ...
;         ss = wave_sum(ss);
;         const float rstd = rsqrtf(ss * (1.0f / D) + EPS);
; #pragma unroll
;         for (int i = 0; i < 4; ++i) {
;             const f32x4 g0 = *(const f32x4*)(p.final_norm_w + i * 512 + lane * 8), g1 = *(const f32x4*)(p.final_norm_w + i * 512 + lane * 8 + 4);
;             f32x4 o0 = {bf_lo(v[i].x), bf_hi(v[i].x), bf_lo(v[i].y), bf_hi(v[i].y)}, o1 = {bf_lo(v[i].z), bf_hi(v[i].z), bf_lo(v[i].w), bf_hi(v[i].w)};
;             __builtin_nontemporal_store(o0 * rstd * g0, (f32x4*)(row + i * 512 + lane * 8)); __builtin_nontemporal_store(o1 * rstd * g1, (f32x4*)(row + i * 512 + lane * 8 + 4));
;         }
	v_add_f32_dpp v84, v84, v84 row_bcast:15 row_mask:0xa bank_mask:0xf
	s_nop 1
	v_add_f32_dpp v84, v84, v84 row_bcast:31 row_mask:0xc bank_mask:0xf
	s_nop 1
	v_readlane_b32 s8, v84, 63
	s_nop 3
	v_mov_b32_e32 v85, s8
	v_fmamk_f32 v85, v85, 0x3a000000, v18
	v_rsq_f32_e32 v85, v85
	s_nop 1
	v_mul_f32_e32 v52, v85, v52
	v_mul_f32_e32 v53, v85, v53
	v_mul_f32_e32 v54, v85, v54
	v_mul_f32_e32 v55, v85, v55
	v_mul_f32_e32 v56, v85, v56
	v_mul_f32_e32 v57, v85, v57
	v_mul_f32_e32 v58, v85, v58
	v_mul_f32_e32 v59, v85, v59
	v_mul_f32_e32 v60, v85, v60
	v_mul_f32_e32 v61, v85, v61
	v_mul_f32_e32 v62, v85, v62
	v_mul_f32_e32 v63, v85, v63
	v_mul_f32_e32 v64, v85, v64
	v_mul_f32_e32 v65, v85, v65
	v_mul_f32_e32 v66, v85, v66
	v_mul_f32_e32 v67, v85, v67
	v_mul_f32_e32 v68, v85, v68
	v_mul_f32_e32 v69, v85, v69
	v_mul_f32_e32 v70, v85, v70
	v_mul_f32_e32 v71, v85, v71
	v_mul_f32_e32 v72, v85, v72
	v_mul_f32_e32 v73, v85, v73
	v_mul_f32_e32 v74, v85, v74
	v_mul_f32_e32 v75, v85, v75
	v_mul_f32_e32 v76, v85, v76
	v_mul_f32_e32 v77, v85, v77
	v_mul_f32_e32 v78, v85, v78
	v_mul_f32_e32 v79, v85, v79
	v_mul_f32_e32 v80, v85, v80
	v_mul_f32_e32 v81, v85, v81
	v_mul_f32_e32 v82, v85, v82
	v_mul_f32_e32 v83, v85, v83
	v_mul_f32_e32 v52, v100, v52
	v_mul_f32_e32 v53, v101, v53
	v_mul_f32_e32 v54, v102, v54
	v_mul_f32_e32 v55, v103, v55
	v_mul_f32_e32 v56, v104, v56
	v_mul_f32_e32 v57, v105, v57
	v_mul_f32_e32 v58, v106, v58
	v_mul_f32_e32 v59, v107, v59
	v_mul_f32_e32 v60, v108, v60
	v_mul_f32_e32 v61, v109, v61
	v_mul_f32_e32 v62, v110, v62
	v_mul_f32_e32 v63, v111, v63
	v_mul_f32_e32 v64, v112, v64
	v_mul_f32_e32 v65, v113, v65
	v_mul_f32_e32 v66, v114, v66
	v_mul_f32_e32 v67, v115, v67
	v_mul_f32_e32 v68, v116, v68
	v_mul_f32_e32 v69, v117, v69
	v_mul_f32_e32 v70, v118, v70
	v_mul_f32_e32 v71, v119, v71
	v_mul_f32_e32 v72, v120, v72
	v_mul_f32_e32 v73, v121, v73
	v_mul_f32_e32 v74, v122, v74
	v_mul_f32_e32 v75, v123, v75
	v_mul_f32_e32 v76, v124, v76
	v_mul_f32_e32 v77, v125, v77
	v_mul_f32_e32 v78, v126, v78
	v_mul_f32_e32 v79, v127, v79
	v_mul_f32_e32 v80, v128, v80
	v_mul_f32_e32 v81, v129, v81
	v_mul_f32_e32 v82, v130, v82
	v_mul_f32_e32 v83, v131, v83
	s_nop 1
	global_store_dwordx4 v13, v[52:55], s[12:13] nt
	global_store_dwordx4 v13, v[56:59], s[12:13] offset:16 nt
	global_store_dwordx4 v13, v[60:63], s[12:13] offset:2048 nt
	global_store_dwordx4 v13, v[64:67], s[12:13] offset:2064 nt
	global_store_dwordx4 v14, v[68:71], s[12:13] nt
	global_store_dwordx4 v14, v[72:75], s[12:13] offset:16 nt
	global_store_dwordx4 v14, v[76:79], s[12:13] offset:2048 nt
	global_store_dwordx4 v14, v[80:83], s[12:13] offset:2064 nt
	s_add_i32 s6, s7, s2
.Lfin_loop:
	s_cmp_lt_i32 s6, 0x8000
	s_cbranch_scc0 .Lfin_tailB
	s_lshl_b32 s8, s6, 12
	s_add_u32 s10, s44, s8
	s_addc_u32 s11, s45, 0
	global_load_dwordx4 v[20:23], v12, s[10:11] nt
	global_load_dwordx4 v[24:27], v12, s[10:11] offset:1024 nt
	global_load_dwordx4 v[28:31], v12, s[10:11] offset:2048 nt
	global_load_dwordx4 v[32:35], v12, s[10:11] offset:3072 nt
	s_waitcnt vmcnt(12)
	v_lshlrev_b32_e32 v52, 16, v36
	v_and_b32_e32 v53, 0xffff0000, v36
	v_lshlrev_b32_e32 v54, 16, v37
	v_and_b32_e32 v55, 0xffff0000, v37
	v_lshlrev_b32_e32 v56, 16, v38
	v_and_b32_e32 v57, 0xffff0000, v38
	v_lshlrev_b32_e32 v58, 16, v39
	v_and_b32_e32 v59, 0xffff0000, v39
	v_lshlrev_b32_e32 v60, 16, v40
	v_and_b32_e32 v61, 0xffff0000, v40
	v_lshlrev_b32_e32 v62, 16, v41
	v_and_b32_e32 v63, 0xffff0000, v41
	v_lshlrev_b32_e32 v64, 16, v42
	v_and_b32_e32 v65, 0xffff0000, v42
	v_lshlrev_b32_e32 v66, 16, v43
	v_and_b32_e32 v67, 0xffff0000, v43
	v_lshlrev_b32_e32 v68, 16, v44
	v_and_b32_e32 v69, 0xffff0000, v44
	v_lshlrev_b32_e32 v70, 16, v45
	v_and_b32_e32 v71, 0xffff0000, v45
	v_lshlrev_b32_e32 v72, 16, v46
	v_and_b32_e32 v73, 0xffff0000, v46
	v_lshlrev_b32_e32 v74, 16, v47
	v_and_b32_e32 v75, 0xffff0000, v47
	v_lshlrev_b32_e32 v76, 16, v48
	v_and_b32_e32 v77, 0xffff0000, v48
	v_lshlrev_b32_e32 v78, 16, v49
	v_and_b32_e32 v79, 0xffff0000, v49
	v_lshlrev_b32_e32 v80, 16, v50
	v_and_b32_e32 v81, 0xffff0000, v50
	v_lshlrev_b32_e32 v82, 16, v51
	v_and_b32_e32 v83, 0xffff0000, v51
	s_lshl_b32 s8, s7, 13
	s_add_u32 s12, s70, s8
	s_addc_u32 s13, s71, 0
	v_mul_f32_e32 v84, v52, v52
	v_mul_f32_e32 v85, v53, v53
	v_mul_f32_e32 v86, v54, v54
	v_mul_f32_e32 v87, v55, v55
	v_fmac_f32_e32 v84, v56, v56
	v_fmac_f32_e32 v85, v57, v57
	v_fmac_f32_e32 v86, v58, v58
	v_fmac_f32_e32 v87, v59, v59
	v_fmac_f32_e32 v84, v60, v60
	v_fmac_f32_e32 v85, v61, v61
	v_fmac_f32_e32 v86, v62, v62
	v_fmac_f32_e32 v87, v63, v63
	v_fmac_f32_e32 v84, v64, v64
	v_fmac_f32_e32 v85, v65, v65
	v_fmac_f32_e32 v86, v66, v66
	v_fmac_f32_e32 v87, v67, v67
	v_fmac_f32_e32 v84, v68, v68
	v_fmac_f32_e32 v85, v69, v69
	v_fmac_f32_e32 v86, v70, v70
	v_fmac_f32_e32 v87, v71, v71
	v_fmac_f32_e32 v84, v72, v72
	v_fmac_f32_e32 v85, v73, v73
	v_fmac_f32_e32 v86, v74, v74
	v_fmac_f32_e32 v87, v75, v75
	v_fmac_f32_e32 v84, v76, v76
	v_fmac_f32_e32 v85, v77, v77
	v_fmac_f32_e32 v86, v78, v78
	v_fmac_f32_e32 v87, v79, v79
	v_fmac_f32_e32 v84, v80, v80
	v_fmac_f32_e32 v85, v81, v81
	v_fmac_f32_e32 v86, v82, v82
	v_fmac_f32_e32 v87, v83, v83
	v_add_f32_e32 v84, v84, v85
	v_add_f32_e32 v86, v86, v87
	v_add_f32_e32 v84, v84, v86
	s_nop 1
	v_add_f32_dpp v84, v84, v84 quad_perm:[1,0,3,2] row_mask:0xf bank_mask:0xf
	s_nop 1
	v_add_f32_dpp v84, v84, v84 quad_perm:[2,3,0,1] row_mask:0xf bank_mask:0xf
	s_nop 1
	v_add_f32_dpp v84, v84, v84 row_ror:4 row_mask:0xf bank_mask:0xf
	s_nop 1
	v_add_f32_dpp v84, v84, v84 row_ror:8 row_mask:0xf bank_mask:0xf
	s_nop 1
	v_add_f32_dpp v84, v84, v84 row_bcast:15 row_mask:0xa bank_mask:0xf
; __device__ __forceinline__ float bf_lo(unsigned u) { return __uint_as_float(u << 16); }
; __device__ __forceinline__ float bf_hi(unsigned u) { return __uint_as_float(u & 0xffff0000u); }
; __device__ void phase_final(const Params& p) {
;     ...
;     for (int r = blockIdx.x * 8 + w; r < T; r += gridDim.x * 8) {
;         const bf16_t* src = x3 + (size_t)r * D;
;         float* row = p.out + (size_t)r * D;
;         u32x4 v[4]; float ss = 0.f;
; #pragma unroll
;         for (int i = 0; i < 4; ++i) {
;             v[i] = __builtin_nontemporal_load((const u32x4*)(src + i * 512 + lane * 8));
;             const float a0 = bf_lo(v[i].x), a1 = bf_hi(v[i].x), a2 = bf_lo(v[i].y), a3 = bf_hi(v[i].y), a4 = bf_lo(v[i].z), a5 = bf_hi(v[i].z), a6 = bf_lo(v[i].w), a7 = bf_hi(v[i].w);
;             ss += a0 * a0 + a1 * a1 + a2 * a2 + a3 * a3 + a4 * a4 + a5 * a5 + a6 * a6 + a7 * a7;
;         }
;         ss = wave_sum(ss);
;         const float rstd = rsqrtf(ss * (1.0f / D) + EPS);
; #pragma unroll
;         for (int i = 0; i < 4; ++i) {
;             const f32x4 g0 = *(const f32x4*)(p.final_norm_w + i * 512 + lane * 8), g1 = *(const f32x4*)(p.final_norm_w + i * 512 + lane * 8 + 4);
;             f32x4 o0 = {bf_lo(v[i].x), bf_hi(v[i].x), bf_lo(v[i].y), bf_hi(v[i].y)}, o1 = {bf_lo(v[i].z), bf_hi(v[i].z), bf_lo(v[i].w), bf_hi(v[i].w)};
;             __builtin_nontemporal_store(o0 * rstd * g0, (f32x4*)(row + i * 512 + lane * 8)); __builtin_nontemporal_store(o1 * rstd * g1, (f32x4*)(row + i * 512 + lane * 8 + 4));
;         }
	s_nop 1
	v_add_f32_dpp v84, v84, v84 row_bcast:31 row_mask:0xc bank_mask:0xf
	s_nop 1
	v_readlane_b32 s8, v84, 63
	s_nop 3
	v_mov_b32_e32 v85, s8
	v_fmamk_f32 v85, v85, 0x3a000000, v18
	v_rsq_f32_e32 v85, v85
	s_nop 1
	v_mul_f32_e32 v52, v85, v52
	v_mul_f32_e32 v53, v85, v53
	v_mul_f32_e32 v54, v85, v54
	v_mul_f32_e32 v55, v85, v55
	v_mul_f32_e32 v56, v85, v56
	v_mul_f32_e32 v57, v85, v57
	v_mul_f32_e32 v58, v85, v58
	v_mul_f32_e32 v59, v85, v59
	v_mul_f32_e32 v60, v85, v60
	v_mul_f32_e32 v61, v85, v61
	v_mul_f32_e32 v62, v85, v62
	v_mul_f32_e32 v63, v85, v63
	v_mul_f32_e32 v64, v85, v64
	v_mul_f32_e32 v65, v85, v65
	v_mul_f32_e32 v66, v85, v66
	v_mul_f32_e32 v67, v85, v67
	v_mul_f32_e32 v68, v85, v68
	v_mul_f32_e32 v69, v85, v69
	v_mul_f32_e32 v70, v85, v70
	v_mul_f32_e32 v71, v85, v71
	v_mul_f32_e32 v72, v85, v72
	v_mul_f32_e32 v73, v85, v73
	v_mul_f32_e32 v74, v85, v74
	v_mul_f32_e32 v75, v85, v75
	v_mul_f32_e32 v76, v85, v76
	v_mul_f32_e32 v77, v85, v77
	v_mul_f32_e32 v78, v85, v78
	v_mul_f32_e32 v79, v85, v79
	v_mul_f32_e32 v80, v85, v80
	v_mul_f32_e32 v81, v85, v81
	v_mul_f32_e32 v82, v85, v82
	v_mul_f32_e32 v83, v85, v83
	v_mul_f32_e32 v52, v100, v52
	v_mul_f32_e32 v53, v101, v53
	v_mul_f32_e32 v54, v102, v54
	v_mul_f32_e32 v55, v103, v55
	v_mul_f32_e32 v56, v104, v56
	v_mul_f32_e32 v57, v105, v57
	v_mul_f32_e32 v58, v106, v58
	v_mul_f32_e32 v59, v107, v59
	v_mul_f32_e32 v60, v108, v60
	v_mul_f32_e32 v61, v109, v61
	v_mul_f32_e32 v62, v110, v62
	v_mul_f32_e32 v63, v111, v63
	v_mul_f32_e32 v64, v112, v64
	v_mul_f32_e32 v65, v113, v65
	v_mul_f32_e32 v66, v114, v66
	v_mul_f32_e32 v67, v115, v67
	v_mul_f32_e32 v68, v116, v68
	v_mul_f32_e32 v69, v117, v69
	v_mul_f32_e32 v70, v118, v70
	v_mul_f32_e32 v71, v119, v71
	v_mul_f32_e32 v72, v120, v72
	v_mul_f32_e32 v73, v121, v73
	v_mul_f32_e32 v74, v122, v74
	v_mul_f32_e32 v75, v123, v75
	v_mul_f32_e32 v76, v124, v76
	v_mul_f32_e32 v77, v125, v77
	v_mul_f32_e32 v78, v126, v78
	v_mul_f32_e32 v79, v127, v79
	v_mul_f32_e32 v80, v128, v80
	v_mul_f32_e32 v81, v129, v81
	v_mul_f32_e32 v82, v130, v82
	v_mul_f32_e32 v83, v131, v83
	s_nop 1
	global_store_dwordx4 v13, v[52:55], s[12:13] nt
	global_store_dwordx4 v13, v[56:59], s[12:13] offset:16 nt
	global_store_dwordx4 v13, v[60:63], s[12:13] offset:2048 nt
	global_store_dwordx4 v13, v[64:67], s[12:13] offset:2064 nt
	global_store_dwordx4 v14, v[68:71], s[12:13] nt
	global_store_dwordx4 v14, v[72:75], s[12:13] offset:16 nt
	global_store_dwordx4 v14, v[76:79], s[12:13] offset:2048 nt
	global_store_dwordx4 v14, v[80:83], s[12:13] offset:2064 nt
	s_add_i32 s7, s6, s2
	s_cmp_lt_i32 s7, 0x8000
	s_cbranch_scc0 .Lfin_tailA
	s_lshl_b32 s8, s7, 12
	s_add_u32 s10, s44, s8
	s_addc_u32 s11, s45, 0
	global_load_dwordx4 v[36:39], v12, s[10:11] nt
	global_load_dwordx4 v[40:43], v12, s[10:11] offset:1024 nt
	global_load_dwordx4 v[44:47], v12, s[10:11] offset:2048 nt
	global_load_dwordx4 v[48:51], v12, s[10:11] offset:3072 nt
	s_waitcnt vmcnt(12)
	v_lshlrev_b32_e32 v52, 16, v20
	v_and_b32_e32 v53, 0xffff0000, v20
	v_lshlrev_b32_e32 v54, 16, v21
	v_and_b32_e32 v55, 0xffff0000, v21
	v_lshlrev_b32_e32 v56, 16, v22
	v_and_b32_e32 v57, 0xffff0000, v22
	v_lshlrev_b32_e32 v58, 16, v23
	v_and_b32_e32 v59, 0xffff0000, v23
	v_lshlrev_b32_e32 v60, 16, v24
	v_and_b32_e32 v61, 0xffff0000, v24
	v_lshlrev_b32_e32 v62, 16, v25
	v_and_b32_e32 v63, 0xffff0000, v25
	v_lshlrev_b32_e32 v64, 16, v26
	v_and_b32_e32 v65, 0xffff0000, v26
	v_lshlrev_b32_e32 v66, 16, v27
	v_and_b32_e32 v67, 0xffff0000, v27
	v_lshlrev_b32_e32 v68, 16, v28
	v_and_b32_e32 v69, 0xffff0000, v28
	v_lshlrev_b32_e32 v70, 16, v29
	v_and_b32_e32 v71, 0xffff0000, v29
	v_lshlrev_b32_e32 v72, 16, v30
	v_and_b32_e32 v73, 0xffff0000, v30
	v_lshlrev_b32_e32 v74, 16, v31
	v_and_b32_e32 v75, 0xffff0000, v31
	v_lshlrev_b32_e32 v76, 16, v32
	v_and_b32_e32 v77, 0xffff0000, v32
	v_lshlrev_b32_e32 v78, 16, v33
	v_and_b32_e32 v79, 0xffff0000, v33
	v_lshlrev_b32_e32 v80, 16, v34
	v_and_b32_e32 v81, 0xffff0000, v34
	v_lshlrev_b32_e32 v82, 16, v35
	v_and_b32_e32 v83, 0xffff0000, v35
	s_lshl_b32 s8, s6, 13
	s_add_u32 s12, s70, s8
	s_addc_u32 s13, s71, 0
	v_mul_f32_e32 v84, v52, v52
	v_mul_f32_e32 v85, v53, v53
	v_mul_f32_e32 v86, v54, v54
	v_mul_f32_e32 v87, v55, v55
	v_fmac_f32_e32 v84, v56, v56
	v_fmac_f32_e32 v85, v57, v57
	v_fmac_f32_e32 v86, v58, v58
	v_fmac_f32_e32 v87, v59, v59
	v_fmac_f32_e32 v84, v60, v60
	v_fmac_f32_e32 v85, v61, v61
	v_fmac_f32_e32 v86, v62, v62
	v_fmac_f32_e32 v87, v63, v63
	v_fmac_f32_e32 v84, v64, v64
	v_fmac_f32_e32 v85, v65, v65
	v_fmac_f32_e32 v86, v66, v66
	v_fmac_f32_e32 v87, v67, v67
	v_fmac_f32_e32 v84, v68, v68
	v_fmac_f32_e32 v85, v69, v69
	v_fmac_f32_e32 v86, v70, v70
	v_fmac_f32_e32 v87, v71, v71
	v_fmac_f32_e32 v84, v72, v72
	v_fmac_f32_e32 v85, v73, v73
	v_fmac_f32_e32 v86, v74, v74
	v_fmac_f32_e32 v87, v75, v75
	v_fmac_f32_e32 v84, v76, v76
	v_fmac_f32_e32 v85, v77, v77
	v_fmac_f32_e32 v86, v78, v78
	v_fmac_f32_e32 v87, v79, v79
	v_fmac_f32_e32 v84, v80, v80
	v_fmac_f32_e32 v85, v81, v81
	v_fmac_f32_e32 v86, v82, v82
	v_fmac_f32_e32 v87, v83, v83
	v_add_f32_e32 v84, v84, v85
	v_add_f32_e32 v86, v86, v87
	v_add_f32_e32 v84, v84, v86
	s_nop 1
	v_add_f32_dpp v84, v84, v84 quad_perm:[1,0,3,2] row_mask:0xf bank_mask:0xf
	s_nop 1
	v_add_f32_dpp v84, v84, v84 quad_perm:[2,3,0,1] row_mask:0xf bank_mask:0xf
	s_nop 1
	v_add_f32_dpp v84, v84, v84 row_ror:4 row_mask:0xf bank_mask:0xf
	s_nop 1
	v_add_f32_dpp v84, v84, v84 row_ror:8 row_mask:0xf bank_mask:0xf
	s_nop 1
	v_add_f32_dpp v84, v84, v84 row_bcast:15 row_mask:0xa bank_mask:0xf
	s_nop 1
	v_add_f32_dpp v84, v84, v84 row_bcast:31 row_mask:0xc bank_mask:0xf
; __device__ __forceinline__ float bf_lo(unsigned u) { return __uint_as_float(u << 16); }
; __device__ __forceinline__ float bf_hi(unsigned u) { return __uint_as_float(u & 0xffff0000u); }
; __device__ void phase_final(const Params& p) {
;     ...
;     for (int r = blockIdx.x * 8 + w; r < T; r += gridDim.x * 8) {
;         const bf16_t* src = x3 + (size_t)r * D;
;         float* row = p.out + (size_t)r * D;
;         u32x4 v[4]; float ss = 0.f;
; #pragma unroll
;         for (int i = 0; i < 4; ++i) {
;             v[i] = __builtin_nontemporal_load((const u32x4*)(src + i * 512 + lane * 8));
;             const float a0 = bf_lo(v[i].x), a1 = bf_hi(v[i].x), a2 = bf_lo(v[i].y), a3 = bf_hi(v[i].y), a4 = bf_lo(v[i].z), a5 = bf_hi(v[i].z), a6 = bf_lo(v[i].w), a7 = bf_hi(v[i].w);
;             ss += a0 * a0 + a1 * a1 + a2 * a2 + a3 * a3 + a4 * a4 + a5 * a5 + a6 * a6 + a7 * a7;
;         }
;         ss = wave_sum(ss);
;         const float rstd = rsqrtf(ss * (1.0f / D) + EPS);
; #pragma unroll
;         for (int i = 0; i < 4; ++i) {
;             const f32x4 g0 = *(const f32x4*)(p.final_norm_w + i * 512 + lane * 8), g1 = *(const f32x4*)(p.final_norm_w + i * 512 + lane * 8 + 4);
;             f32x4 o0 = {bf_lo(v[i].x), bf_hi(v[i].x), bf_lo(v[i].y), bf_hi(v[i].y)}, o1 = {bf_lo(v[i].z), bf_hi(v[i].z), bf_lo(v[i].w), bf_hi(v[i].w)};
;             __builtin_nontemporal_store(o0 * rstd * g0, (f32x4*)(row + i * 512 + lane * 8)); __builtin_nontemporal_store(o1 * rstd * g1, (f32x4*)(row + i * 512 + lane * 8 + 4));
;         }
	s_nop 1
	v_readlane_b32 s8, v84, 63
	s_nop 3
	v_mov_b32_e32 v85, s8
	v_fmamk_f32 v85, v85, 0x3a000000, v18
	v_rsq_f32_e32 v85, v85
	s_nop 1
	v_mul_f32_e32 v52, v85, v52
	v_mul_f32_e32 v53, v85, v53
	v_mul_f32_e32 v54, v85, v54
	v_mul_f32_e32 v55, v85, v55
	v_mul_f32_e32 v56, v85, v56
	v_mul_f32_e32 v57, v85, v57
	v_mul_f32_e32 v58, v85, v58
	v_mul_f32_e32 v59, v85, v59
	v_mul_f32_e32 v60, v85, v60
	v_mul_f32_e32 v61, v85, v61
	v_mul_f32_e32 v62, v85, v62
	v_mul_f32_e32 v63, v85, v63
	v_mul_f32_e32 v64, v85, v64
	v_mul_f32_e32 v65, v85, v65
	v_mul_f32_e32 v66, v85, v66
	v_mul_f32_e32 v67, v85, v67
	v_mul_f32_e32 v68, v85, v68
	v_mul_f32_e32 v69, v85, v69
	v_mul_f32_e32 v70, v85, v70
	v_mul_f32_e32 v71, v85, v71
	v_mul_f32_e32 v72, v85, v72
	v_mul_f32_e32 v73, v85, v73
	v_mul_f32_e32 v74, v85, v74
	v_mul_f32_e32 v75, v85, v75
	v_mul_f32_e32 v76, v85, v76
	v_mul_f32_e32 v77, v85, v77
	v_mul_f32_e32 v78, v85, v78
	v_mul_f32_e32 v79, v85, v79
	v_mul_f32_e32 v80, v85, v80
	v_mul_f32_e32 v81, v85, v81
	v_mul_f32_e32 v82, v85, v82
	v_mul_f32_e32 v83, v85, v83
	v_mul_f32_e32 v52, v100, v52
	v_mul_f32_e32 v53, v101, v53
	v_mul_f32_e32 v54, v102, v54
	v_mul_f32_e32 v55, v103, v55
	v_mul_f32_e32 v56, v104, v56
	v_mul_f32_e32 v57, v105, v57
	v_mul_f32_e32 v58, v106, v58
	v_mul_f32_e32 v59, v107, v59
	v_mul_f32_e32 v60, v108, v60
	v_mul_f32_e32 v61, v109, v61
	v_mul_f32_e32 v62, v110, v62
	v_mul_f32_e32 v63, v111, v63
	v_mul_f32_e32 v64, v112, v64
	v_mul_f32_e32 v65, v113, v65
	v_mul_f32_e32 v66, v114, v66
	v_mul_f32_e32 v67, v115, v67
	v_mul_f32_e32 v68, v116, v68
	v_mul_f32_e32 v69, v117, v69
	v_mul_f32_e32 v70, v118, v70
	v_mul_f32_e32 v71, v119, v71
	v_mul_f32_e32 v72, v120, v72
	v_mul_f32_e32 v73, v121, v73
	v_mul_f32_e32 v74, v122, v74
	v_mul_f32_e32 v75, v123, v75
	v_mul_f32_e32 v76, v124, v76
	v_mul_f32_e32 v77, v125, v77
	v_mul_f32_e32 v78, v126, v78
	v_mul_f32_e32 v79, v127, v79
	v_mul_f32_e32 v80, v128, v80
	v_mul_f32_e32 v81, v129, v81
	v_mul_f32_e32 v82, v130, v82
	v_mul_f32_e32 v83, v131, v83
	s_nop 1
	global_store_dwordx4 v13, v[52:55], s[12:13] nt
	global_store_dwordx4 v13, v[56:59], s[12:13] offset:16 nt
	global_store_dwordx4 v13, v[60:63], s[12:13] offset:2048 nt
	global_store_dwordx4 v13, v[64:67], s[12:13] offset:2064 nt
	global_store_dwordx4 v14, v[68:71], s[12:13] nt
	global_store_dwordx4 v14, v[72:75], s[12:13] offset:16 nt
	global_store_dwordx4 v14, v[76:79], s[12:13] offset:2048 nt
	global_store_dwordx4 v14, v[80:83], s[12:13] offset:2064 nt
	s_add_i32 s6, s7, s2
	s_branch .Lfin_loop
.Lfin_tailB:
	s_waitcnt vmcnt(0)
	v_lshlrev_b32_e32 v52, 16, v36
	v_and_b32_e32 v53, 0xffff0000, v36
	v_lshlrev_b32_e32 v54, 16, v37
	v_and_b32_e32 v55, 0xffff0000, v37
	v_lshlrev_b32_e32 v56, 16, v38
	v_and_b32_e32 v57, 0xffff0000, v38
	v_lshlrev_b32_e32 v58, 16, v39
	v_and_b32_e32 v59, 0xffff0000, v39
	v_lshlrev_b32_e32 v60, 16, v40
	v_and_b32_e32 v61, 0xffff0000, v40
	v_lshlrev_b32_e32 v62, 16, v41
	v_and_b32_e32 v63, 0xffff0000, v41
	v_lshlrev_b32_e32 v64, 16, v42
	v_and_b32_e32 v65, 0xffff0000, v42
	v_lshlrev_b32_e32 v66, 16, v43
	v_and_b32_e32 v67, 0xffff0000, v43
	v_lshlrev_b32_e32 v68, 16, v44
	v_and_b32_e32 v69, 0xffff0000, v44
	v_lshlrev_b32_e32 v70, 16, v45
	v_and_b32_e32 v71, 0xffff0000, v45
	v_lshlrev_b32_e32 v72, 16, v46
	v_and_b32_e32 v73, 0xffff0000, v46
	v_lshlrev_b32_e32 v74, 16, v47
	v_and_b32_e32 v75, 0xffff0000, v47
	v_lshlrev_b32_e32 v76, 16, v48
	v_and_b32_e32 v77, 0xffff0000, v48
	v_lshlrev_b32_e32 v78, 16, v49
	v_and_b32_e32 v79, 0xffff0000, v49
	v_lshlrev_b32_e32 v80, 16, v50
	v_and_b32_e32 v81, 0xffff0000, v50
	v_lshlrev_b32_e32 v82, 16, v51
	v_and_b32_e32 v83, 0xffff0000, v51
	s_lshl_b32 s8, s7, 13
	s_add_u32 s12, s70, s8
	s_addc_u32 s13, s71, 0
	v_mul_f32_e32 v84, v52, v52
	v_mul_f32_e32 v85, v53, v53
	v_mul_f32_e32 v86, v54, v54
	v_mul_f32_e32 v87, v55, v55
	v_fmac_f32_e32 v84, v56, v56
	v_fmac_f32_e32 v85, v57, v57
	v_fmac_f32_e32 v86, v58, v58
	v_fmac_f32_e32 v87, v59, v59
	v_fmac_f32_e32 v84, v60, v60
	v_fmac_f32_e32 v85, v61, v61
	v_fmac_f32_e32 v86, v62, v62
	v_fmac_f32_e32 v87, v63, v63
	v_fmac_f32_e32 v84, v64, v64
	v_fmac_f32_e32 v85, v65, v65
	v_fmac_f32_e32 v86, v66, v66
	v_fmac_f32_e32 v87, v67, v67
	v_fmac_f32_e32 v84, v68, v68
	v_fmac_f32_e32 v85, v69, v69
	v_fmac_f32_e32 v86, v70, v70
	v_fmac_f32_e32 v87, v71, v71
	v_fmac_f32_e32 v84, v72, v72
	v_fmac_f32_e32 v85, v73, v73
	v_fmac_f32_e32 v86, v74, v74
	v_fmac_f32_e32 v87, v75, v75
	v_fmac_f32_e32 v84, v76, v76
	v_fmac_f32_e32 v85, v77, v77
	v_fmac_f32_e32 v86, v78, v78
	v_fmac_f32_e32 v87, v79, v79
	v_fmac_f32_e32 v84, v80, v80
	v_fmac_f32_e32 v85, v81, v81
	v_fmac_f32_e32 v86, v82, v82
	v_fmac_f32_e32 v87, v83, v83
	v_add_f32_e32 v84, v84, v85
	v_add_f32_e32 v86, v86, v87
	v_add_f32_e32 v84, v84, v86
	s_nop 1
	v_add_f32_dpp v84, v84, v84 quad_perm:[1,0,3,2] row_mask:0xf bank_mask:0xf
	s_nop 1
	v_add_f32_dpp v84, v84, v84 quad_perm:[2,3,0,1] row_mask:0xf bank_mask:0xf
	s_nop 1
	v_add_f32_dpp v84, v84, v84 row_ror:4 row_mask:0xf bank_mask:0xf
	s_nop 1
	v_add_f32_dpp v84, v84, v84 row_ror:8 row_mask:0xf bank_mask:0xf
	s_nop 1
	v_add_f32_dpp v84, v84, v84 row_bcast:15 row_mask:0xa bank_mask:0xf
	s_nop 1
	v_add_f32_dpp v84, v84, v84 row_bcast:31 row_mask:0xc bank_mask:0xf
	s_nop 1
	v_readlane_b32 s8, v84, 63
	s_nop 3
	v_mov_b32_e32 v85, s8
	v_fmamk_f32 v85, v85, 0x3a000000, v18
	v_rsq_f32_e32 v85, v85
	s_nop 1
	v_mul_f32_e32 v52, v85, v52
	v_mul_f32_e32 v53, v85, v53
	v_mul_f32_e32 v54, v85, v54
	v_mul_f32_e32 v55, v85, v55
	v_mul_f32_e32 v56, v85, v56
	v_mul_f32_e32 v57, v85, v57
	v_mul_f32_e32 v58, v85, v58
	v_mul_f32_e32 v59, v85, v59
	v_mul_f32_e32 v60, v85, v60
; __device__ __forceinline__ float bf_lo(unsigned u) { return __uint_as_float(u << 16); }
; __device__ __forceinline__ float bf_hi(unsigned u) { return __uint_as_float(u & 0xffff0000u); }
; __device__ void phase_final(const Params& p) {
;     ...
;         const float rstd = rsqrtf(ss * (1.0f / D) + EPS);
; #pragma unroll
;         for (int i = 0; i < 4; ++i) {
;             const f32x4 g0 = *(const f32x4*)(p.final_norm_w + i * 512 + lane * 8), g1 = *(const f32x4*)(p.final_norm_w + i * 512 + lane * 8 + 4);
;             f32x4 o0 = {bf_lo(v[i].x), bf_hi(v[i].x), bf_lo(v[i].y), bf_hi(v[i].y)}, o1 = {bf_lo(v[i].z), bf_hi(v[i].z), bf_lo(v[i].w), bf_hi(v[i].w)};
;             __builtin_nontemporal_store(o0 * rstd * g0, (f32x4*)(row + i * 512 + lane * 8)); __builtin_nontemporal_store(o1 * rstd * g1, (f32x4*)(row + i * 512 + lane * 8 + 4));
;         }
	v_mul_f32_e32 v61, v85, v61
	v_mul_f32_e32 v62, v85, v62
	v_mul_f32_e32 v63, v85, v63
	v_mul_f32_e32 v64, v85, v64
	v_mul_f32_e32 v65, v85, v65
	v_mul_f32_e32 v66, v85, v66
	v_mul_f32_e32 v67, v85, v67
	v_mul_f32_e32 v68, v85, v68
	v_mul_f32_e32 v69, v85, v69
	v_mul_f32_e32 v70, v85, v70
	v_mul_f32_e32 v71, v85, v71
	v_mul_f32_e32 v72, v85, v72
	v_mul_f32_e32 v73, v85, v73
	v_mul_f32_e32 v74, v85, v74
	v_mul_f32_e32 v75, v85, v75
	v_mul_f32_e32 v76, v85, v76
	v_mul_f32_e32 v77, v85, v77
	v_mul_f32_e32 v78, v85, v78
	v_mul_f32_e32 v79, v85, v79
	v_mul_f32_e32 v80, v85, v80
	v_mul_f32_e32 v81, v85, v81
	v_mul_f32_e32 v82, v85, v82
	v_mul_f32_e32 v83, v85, v83
	v_mul_f32_e32 v52, v100, v52
	v_mul_f32_e32 v53, v101, v53
	v_mul_f32_e32 v54, v102, v54
	v_mul_f32_e32 v55, v103, v55
	v_mul_f32_e32 v56, v104, v56
	v_mul_f32_e32 v57, v105, v57
	v_mul_f32_e32 v58, v106, v58
	v_mul_f32_e32 v59, v107, v59
	v_mul_f32_e32 v60, v108, v60
	v_mul_f32_e32 v61, v109, v61
	v_mul_f32_e32 v62, v110, v62
	v_mul_f32_e32 v63, v111, v63
	v_mul_f32_e32 v64, v112, v64
	v_mul_f32_e32 v65, v113, v65
	v_mul_f32_e32 v66, v114, v66
	v_mul_f32_e32 v67, v115, v67
	v_mul_f32_e32 v68, v116, v68
	v_mul_f32_e32 v69, v117, v69
	v_mul_f32_e32 v70, v118, v70
	v_mul_f32_e32 v71, v119, v71
	v_mul_f32_e32 v72, v120, v72
	v_mul_f32_e32 v73, v121, v73
	v_mul_f32_e32 v74, v122, v74
	v_mul_f32_e32 v75, v123, v75
	v_mul_f32_e32 v76, v124, v76
	v_mul_f32_e32 v77, v125, v77
	v_mul_f32_e32 v78, v126, v78
	v_mul_f32_e32 v79, v127, v79
	v_mul_f32_e32 v80, v128, v80
	v_mul_f32_e32 v81, v129, v81
	v_mul_f32_e32 v82, v130, v82
	v_mul_f32_e32 v83, v131, v83
	s_nop 1
	global_store_dwordx4 v13, v[52:55], s[12:13] nt
	global_store_dwordx4 v13, v[56:59], s[12:13] offset:16 nt
	global_store_dwordx4 v13, v[60:63], s[12:13] offset:2048 nt
	global_store_dwordx4 v13, v[64:67], s[12:13] offset:2064 nt
	global_store_dwordx4 v14, v[68:71], s[12:13] nt
	global_store_dwordx4 v14, v[72:75], s[12:13] offset:16 nt
	global_store_dwordx4 v14, v[76:79], s[12:13] offset:2048 nt
	global_store_dwordx4 v14, v[80:83], s[12:13] offset:2064 nt
	s_branch .LBB0_1088
; __device__ __forceinline__ float bf_lo(unsigned u) { return __uint_as_float(u << 16); }
; __device__ __forceinline__ float bf_hi(unsigned u) { return __uint_as_float(u & 0xffff0000u); }
; __device__ void phase_final(const Params& p) {
;     ...
;     for (int r = blockIdx.x * 8 + w; r < T; r += gridDim.x * 8) {
;         const bf16_t* src = x3 + (size_t)r * D;
;         float* row = p.out + (size_t)r * D;
;         u32x4 v[4]; float ss = 0.f;
; #pragma unroll
;         for (int i = 0; i < 4; ++i) {
;             v[i] = __builtin_nontemporal_load((const u32x4*)(src + i * 512 + lane * 8));
;             const float a0 = bf_lo(v[i].x), a1 = bf_hi(v[i].x), a2 = bf_lo(v[i].y), a3 = bf_hi(v[i].y), a4 = bf_lo(v[i].z), a5 = bf_hi(v[i].z), a6 = bf_lo(v[i].w), a7 = bf_hi(v[i].w);
;             ss += a0 * a0 + a1 * a1 + a2 * a2 + a3 * a3 + a4 * a4 + a5 * a5 + a6 * a6 + a7 * a7;
;         }
;         ss = wave_sum(ss);
;         const float rstd = rsqrtf(ss * (1.0f / D) + EPS);
; #pragma unroll
;         for (int i = 0; i < 4; ++i) {
;             const f32x4 g0 = *(const f32x4*)(p.final_norm_w + i * 512 + lane * 8), g1 = *(const f32x4*)(p.final_norm_w + i * 512 + lane * 8 + 4);
;             f32x4 o0 = {bf_lo(v[i].x), bf_hi(v[i].x), bf_lo(v[i].y), bf_hi(v[i].y)}, o1 = {bf_lo(v[i].z), bf_hi(v[i].z), bf_lo(v[i].w), bf_hi(v[i].w)};
;             __builtin_nontemporal_store(o0 * rstd * g0, (f32x4*)(row + i * 512 + lane * 8)); __builtin_nontemporal_store(o1 * rstd * g1, (f32x4*)(row + i * 512 + lane * 8 + 4));
;         }
.Lfin_tailA:
	s_waitcnt vmcnt(0)
	v_lshlrev_b32_e32 v52, 16, v20
	v_and_b32_e32 v53, 0xffff0000, v20
	v_lshlrev_b32_e32 v54, 16, v21
	v_and_b32_e32 v55, 0xffff0000, v21
	v_lshlrev_b32_e32 v56, 16, v22
	v_and_b32_e32 v57, 0xffff0000, v22
	v_lshlrev_b32_e32 v58, 16, v23
	v_and_b32_e32 v59, 0xffff0000, v23
	v_lshlrev_b32_e32 v60, 16, v24
	v_and_b32_e32 v61, 0xffff0000, v24
	v_lshlrev_b32_e32 v62, 16, v25
	v_and_b32_e32 v63, 0xffff0000, v25
	v_lshlrev_b32_e32 v64, 16, v26
	v_and_b32_e32 v65, 0xffff0000, v26
	v_lshlrev_b32_e32 v66, 16, v27
	v_and_b32_e32 v67, 0xffff0000, v27
	v_lshlrev_b32_e32 v68, 16, v28
	v_and_b32_e32 v69, 0xffff0000, v28
	v_lshlrev_b32_e32 v70, 16, v29
	v_and_b32_e32 v71, 0xffff0000, v29
	v_lshlrev_b32_e32 v72, 16, v30
	v_and_b32_e32 v73, 0xffff0000, v30
	v_lshlrev_b32_e32 v74, 16, v31
	v_and_b32_e32 v75, 0xffff0000, v31
	v_lshlrev_b32_e32 v76, 16, v32
	v_and_b32_e32 v77, 0xffff0000, v32
	v_lshlrev_b32_e32 v78, 16, v33
	v_and_b32_e32 v79, 0xffff0000, v33
	v_lshlrev_b32_e32 v80, 16, v34
	v_and_b32_e32 v81, 0xffff0000, v34
	v_lshlrev_b32_e32 v82, 16, v35
	v_and_b32_e32 v83, 0xffff0000, v35
	s_lshl_b32 s8, s6, 13
	s_add_u32 s12, s70, s8
	s_addc_u32 s13, s71, 0
	v_mul_f32_e32 v84, v52, v52
	v_mul_f32_e32 v85, v53, v53
	v_mul_f32_e32 v86, v54, v54
	v_mul_f32_e32 v87, v55, v55
	v_fmac_f32_e32 v84, v56, v56
	v_fmac_f32_e32 v85, v57, v57
	v_fmac_f32_e32 v86, v58, v58
	v_fmac_f32_e32 v87, v59, v59
	v_fmac_f32_e32 v84, v60, v60
	v_fmac_f32_e32 v85, v61, v61
	v_fmac_f32_e32 v86, v62, v62
	v_fmac_f32_e32 v87, v63, v63
	v_fmac_f32_e32 v84, v64, v64
	v_fmac_f32_e32 v85, v65, v65
	v_fmac_f32_e32 v86, v66, v66
	v_fmac_f32_e32 v87, v67, v67
	v_fmac_f32_e32 v84, v68, v68
	v_fmac_f32_e32 v85, v69, v69
	v_fmac_f32_e32 v86, v70, v70
	v_fmac_f32_e32 v87, v71, v71
	v_fmac_f32_e32 v84, v72, v72
	v_fmac_f32_e32 v85, v73, v73
	v_fmac_f32_e32 v86, v74, v74
	v_fmac_f32_e32 v87, v75, v75
	v_fmac_f32_e32 v84, v76, v76
	v_fmac_f32_e32 v85, v77, v77
	v_fmac_f32_e32 v86, v78, v78
	v_fmac_f32_e32 v87, v79, v79
	v_fmac_f32_e32 v84, v80, v80
	v_fmac_f32_e32 v85, v81, v81
	v_fmac_f32_e32 v86, v82, v82
	v_fmac_f32_e32 v87, v83, v83
	v_add_f32_e32 v84, v84, v85
	v_add_f32_e32 v86, v86, v87
	v_add_f32_e32 v84, v84, v86
	s_nop 1
	v_add_f32_dpp v84, v84, v84 quad_perm:[1,0,3,2] row_mask:0xf bank_mask:0xf
	s_nop 1
	v_add_f32_dpp v84, v84, v84 quad_perm:[2,3,0,1] row_mask:0xf bank_mask:0xf
	s_nop 1
	v_add_f32_dpp v84, v84, v84 row_ror:4 row_mask:0xf bank_mask:0xf
	s_nop 1
	v_add_f32_dpp v84, v84, v84 row_ror:8 row_mask:0xf bank_mask:0xf
	s_nop 1
	v_add_f32_dpp v84, v84, v84 row_bcast:15 row_mask:0xa bank_mask:0xf
	s_nop 1
	v_add_f32_dpp v84, v84, v84 row_bcast:31 row_mask:0xc bank_mask:0xf
	s_nop 1
	v_readlane_b32 s8, v84, 63
	s_nop 3
	v_mov_b32_e32 v85, s8
	v_fmamk_f32 v85, v85, 0x3a000000, v18
	v_rsq_f32_e32 v85, v85
	s_nop 1
	v_mul_f32_e32 v52, v85, v52
	v_mul_f32_e32 v53, v85, v53
	v_mul_f32_e32 v54, v85, v54
	v_mul_f32_e32 v55, v85, v55
	v_mul_f32_e32 v56, v85, v56
	v_mul_f32_e32 v57, v85, v57
	v_mul_f32_e32 v58, v85, v58
	v_mul_f32_e32 v59, v85, v59
	v_mul_f32_e32 v60, v85, v60
	v_mul_f32_e32 v61, v85, v61
	v_mul_f32_e32 v62, v85, v62
	v_mul_f32_e32 v63, v85, v63
	v_mul_f32_e32 v64, v85, v64
	v_mul_f32_e32 v65, v85, v65
	v_mul_f32_e32 v66, v85, v66
	v_mul_f32_e32 v67, v85, v67
	v_mul_f32_e32 v68, v85, v68
	v_mul_f32_e32 v69, v85, v69
	v_mul_f32_e32 v70, v85, v70
	v_mul_f32_e32 v71, v85, v71
	v_mul_f32_e32 v72, v85, v72
	v_mul_f32_e32 v73, v85, v73
	v_mul_f32_e32 v74, v85, v74
	v_mul_f32_e32 v75, v85, v75
	v_mul_f32_e32 v76, v85, v76
	v_mul_f32_e32 v77, v85, v77
	v_mul_f32_e32 v78, v85, v78
	v_mul_f32_e32 v79, v85, v79
	v_mul_f32_e32 v80, v85, v80
	v_mul_f32_e32 v81, v85, v81
	v_mul_f32_e32 v82, v85, v82
	v_mul_f32_e32 v83, v85, v83
	v_mul_f32_e32 v52, v100, v52
	v_mul_f32_e32 v53, v101, v53
	v_mul_f32_e32 v54, v102, v54
	v_mul_f32_e32 v55, v103, v55
	v_mul_f32_e32 v56, v104, v56
	v_mul_f32_e32 v57, v105, v57
	v_mul_f32_e32 v58, v106, v58
	v_mul_f32_e32 v59, v107, v59
	v_mul_f32_e32 v60, v108, v60
	v_mul_f32_e32 v61, v109, v61
	v_mul_f32_e32 v62, v110, v62
	v_mul_f32_e32 v63, v111, v63
	v_mul_f32_e32 v64, v112, v64
	v_mul_f32_e32 v65, v113, v65
	v_mul_f32_e32 v66, v114, v66
	v_mul_f32_e32 v67, v115, v67
	v_mul_f32_e32 v68, v116, v68
	v_mul_f32_e32 v69, v117, v69
	v_mul_f32_e32 v70, v118, v70
	v_mul_f32_e32 v71, v119, v71
	v_mul_f32_e32 v72, v120, v72
	v_mul_f32_e32 v73, v121, v73
	v_mul_f32_e32 v74, v122, v74
	v_mul_f32_e32 v75, v123, v75
	v_mul_f32_e32 v76, v124, v76
	v_mul_f32_e32 v77, v125, v77
	v_mul_f32_e32 v78, v126, v78
	v_mul_f32_e32 v79, v127, v79
	v_mul_f32_e32 v80, v128, v80
	v_mul_f32_e32 v81, v129, v81
	v_mul_f32_e32 v82, v130, v82
	v_mul_f32_e32 v83, v131, v83
	s_nop 1
	global_store_dwordx4 v13, v[52:55], s[12:13] nt
	global_store_dwordx4 v13, v[56:59], s[12:13] offset:16 nt
	global_store_dwordx4 v13, v[60:63], s[12:13] offset:2048 nt
	global_store_dwordx4 v13, v[64:67], s[12:13] offset:2064 nt
	global_store_dwordx4 v14, v[68:71], s[12:13] nt
	global_store_dwordx4 v14, v[72:75], s[12:13] offset:16 nt
	global_store_dwordx4 v14, v[76:79], s[12:13] offset:2048 nt
	global_store_dwordx4 v14, v[80:83], s[12:13] offset:2064 nt
